# stagger0 + unused bj=1 MFMAs removed from the SSM chunk-state GEMM
# speedup vs baseline: 1.0046x; 1.0008x over previous
.LBB0_379:
	s_waitcnt lgkmcnt(0)
	s_add_i32 s2, s23, 0x100
	s_add_i32 s3, s4, 0x100
	s_barrier
	s_setprio 1
	s_waitcnt lgkmcnt(7)
	v_mfma_f32_16x16x32_bf16 v[126:129], v[158:161], v[186:189], 0
	v_mfma_f32_16x16x32_bf16 v[122:125], v[150:153], v[186:189], 0
	s_waitcnt lgkmcnt(6)
	v_mfma_f32_16x16x32_bf16 v[118:121], v[158:161], v[178:181], 0
	v_mfma_f32_16x16x32_bf16 v[114:117], v[150:153], v[178:181], 0
	s_waitcnt lgkmcnt(3)
	v_mfma_f32_16x16x32_bf16 v[110:113], v[158:161], v[170:173], 0
	v_mfma_f32_16x16x32_bf16 v[106:109], v[150:153], v[170:173], 0
	s_waitcnt lgkmcnt(2)
	v_mfma_f32_16x16x32_bf16 v[102:105], v[158:161], v[162:165], 0
	v_mfma_f32_16x16x32_bf16 v[98:101], v[150:153], v[162:165], 0
	v_mfma_f32_16x16x32_bf16 v[126:129], v[154:157], v[190:193], v[126:129]
	v_mfma_f32_16x16x32_bf16 v[122:125], v[146:149], v[190:193], v[122:125]
	v_mfma_f32_16x16x32_bf16 v[118:121], v[154:157], v[182:185], v[118:121]
	v_mfma_f32_16x16x32_bf16 v[114:117], v[146:149], v[182:185], v[114:117]
	s_waitcnt lgkmcnt(1)
	v_mfma_f32_16x16x32_bf16 v[110:113], v[154:157], v[174:177], v[110:113]
	v_mfma_f32_16x16x32_bf16 v[106:109], v[146:149], v[174:177], v[106:109]
	s_waitcnt lgkmcnt(0)
	v_mfma_f32_16x16x32_bf16 v[102:105], v[154:157], v[166:169], v[102:105]
	v_mfma_f32_16x16x32_bf16 v[98:101], v[146:149], v[166:169], v[98:101]
	s_setprio 0
	s_setprio 1
	s_nop 0
	s_setprio 0
	s_barrier
	s_mov_b32 m0, s28
	ds_read_b128 v[186:189], v216 offset:16384
	ds_read_b128 v[178:181], v216 offset:18432
	ds_read_b128 v[190:193], v217 offset:16384
	ds_read_b128 v[182:185], v217 offset:18432
	ds_read_b128 v[170:173], v216 offset:20480
	ds_read_b128 v[162:165], v216 offset:22528
	ds_read_b128 v[174:177], v217 offset:20480
	ds_read_b128 v[166:169], v217 offset:22528
	buffer_load_dwordx4 v203, s[8:11], s3 offen lds
	s_mov_b32 m0, s29
	v_cndmask_b32_e64 v218, 0, 1, s[24:25]
	buffer_load_dwordx4 v205, s[8:11], s3 offen lds
	s_add_i32 s3, s4, 0x10100
	s_mov_b32 m0, s30
	s_andn2_b64 vcc, exec, s[24:25]
	buffer_load_dwordx4 v203, s[8:11], s3 offen lds
	s_mov_b32 m0, s31
	s_mov_b64 s[24:25], -1
	buffer_load_dwordx4 v205, s[8:11], s3 offen lds
	s_mov_b32 m0, s27
	s_nop 0
	buffer_load_dwordx4 v198, s[8:11], s2 offen lds
	s_mov_b32 m0, s34
	s_nop 0
	buffer_load_dwordx4 v204, s[8:11], s2 offen lds
	v_cmp_ne_u32_e64 s[2:3], 1, v218
	s_cbranch_vccnz .LBB0_381
	s_waitcnt vmcnt(22)
	s_mov_b64 s[24:25], 0

.LBB0_383:
	s_waitcnt lgkmcnt(0)
	s_barrier
	s_setprio 1
	s_waitcnt lgkmcnt(7)
	v_mfma_f32_16x16x32_bf16 v[62:65], v[158:161], v[186:189], 0
	v_mfma_f32_16x16x32_bf16 v[58:61], v[150:153], v[186:189], 0
	s_waitcnt lgkmcnt(6)
	v_mfma_f32_16x16x32_bf16 v[54:57], v[158:161], v[178:181], 0
	v_mfma_f32_16x16x32_bf16 v[50:53], v[150:153], v[178:181], 0
	s_waitcnt lgkmcnt(3)
	v_mfma_f32_16x16x32_bf16 v[46:49], v[158:161], v[170:173], 0
	v_mfma_f32_16x16x32_bf16 v[42:45], v[150:153], v[170:173], 0
	s_waitcnt lgkmcnt(2)
	v_mfma_f32_16x16x32_bf16 v[38:41], v[158:161], v[162:165], 0
	v_mfma_f32_16x16x32_bf16 v[34:37], v[150:153], v[162:165], 0
	v_mfma_f32_16x16x32_bf16 v[62:65], v[154:157], v[190:193], v[62:65]
	v_mfma_f32_16x16x32_bf16 v[58:61], v[146:149], v[190:193], v[58:61]
	v_mfma_f32_16x16x32_bf16 v[54:57], v[154:157], v[182:185], v[54:57]
	v_mfma_f32_16x16x32_bf16 v[50:53], v[146:149], v[182:185], v[50:53]
	s_waitcnt lgkmcnt(1)
	v_mfma_f32_16x16x32_bf16 v[46:49], v[154:157], v[174:177], v[46:49]
	v_mfma_f32_16x16x32_bf16 v[42:45], v[146:149], v[174:177], v[42:45]
	s_waitcnt lgkmcnt(0)
	v_mfma_f32_16x16x32_bf16 v[38:41], v[154:157], v[166:169], v[38:41]
	v_mfma_f32_16x16x32_bf16 v[34:37], v[146:149], v[166:169], v[34:37]
	s_setprio 0
	s_setprio 1
	s_nop 0
	s_setprio 0
	s_barrier
	v_add_u32_e32 v218, s48, v206
	v_add_u32_e32 v220, s49, v206
	v_add_u32_e32 v222, s50, v206
	v_add_u32_e32 v224, s51, v206
	v_add_u32_e32 v219, s48, v207
	ds_read_b128 v[146:149], v218
	ds_read_b128 v[150:153], v219
	v_add_u32_e32 v221, s49, v207
	ds_read_b128 v[154:157], v220
	ds_read_b128 v[158:161], v221
	v_add_u32_e32 v223, s50, v207
	ds_read_b128 v[130:133], v222
	ds_read_b128 v[134:137], v223
	v_add_u32_e32 v225, s51, v207
	ds_read_b128 v[138:141], v224
	ds_read_b128 v[142:145], v225
	s_mov_b32 m0, s35
	s_add_i32 s24, s23, 0xd00
	ds_read_b128 v[186:189], v216 offset:32768
	ds_read_b128 v[174:177], v216 offset:34816
	ds_read_b128 v[190:193], v217 offset:32768
	ds_read_b128 v[178:181], v217 offset:34816
	ds_read_b128 v[170:173], v216 offset:36864
	ds_read_b128 v[162:165], v216 offset:38912
	ds_read_b128 v[182:185], v217 offset:36864
	ds_read_b128 v[166:169], v217 offset:38912
	buffer_load_dwordx4 v198, s[8:11], s24 offen lds
	s_mov_b32 m0, s36
	s_and_b64 vcc, exec, s[2:3]
	buffer_load_dwordx4 v204, s[8:11], s24 offen lds
	s_mov_b64 s[24:25], -1
	s_cbranch_vccnz .LBB0_385
	s_waitcnt vmcnt(24)
	s_mov_b64 s[24:25], 0

.LBB0_387:
	s_waitcnt lgkmcnt(0)
	s_add_i32 s24, s23, 0x180
	s_add_i32 s25, s4, 0x180
	s_barrier
	s_setprio 1
	s_waitcnt lgkmcnt(7)
	v_mfma_f32_16x16x32_bf16 v[126:129], v[146:149], v[186:189], v[126:129]
	v_mfma_f32_16x16x32_bf16 v[122:125], v[154:157], v[186:189], v[122:125]
	s_waitcnt lgkmcnt(6)
	v_mfma_f32_16x16x32_bf16 v[118:121], v[146:149], v[174:177], v[118:121]
	v_mfma_f32_16x16x32_bf16 v[114:117], v[154:157], v[174:177], v[114:117]
	s_waitcnt lgkmcnt(3)
	v_mfma_f32_16x16x32_bf16 v[110:113], v[146:149], v[170:173], v[110:113]
	v_mfma_f32_16x16x32_bf16 v[106:109], v[154:157], v[170:173], v[106:109]
	s_waitcnt lgkmcnt(2)
	v_mfma_f32_16x16x32_bf16 v[102:105], v[146:149], v[162:165], v[102:105]
	v_mfma_f32_16x16x32_bf16 v[98:101], v[154:157], v[162:165], v[98:101]
	v_mfma_f32_16x16x32_bf16 v[126:129], v[150:153], v[190:193], v[126:129]
	v_mfma_f32_16x16x32_bf16 v[122:125], v[158:161], v[190:193], v[122:125]
	v_mfma_f32_16x16x32_bf16 v[118:121], v[150:153], v[178:181], v[118:121]
	v_mfma_f32_16x16x32_bf16 v[114:117], v[158:161], v[178:181], v[114:117]
	s_waitcnt lgkmcnt(1)
	v_mfma_f32_16x16x32_bf16 v[110:113], v[150:153], v[182:185], v[110:113]
	v_mfma_f32_16x16x32_bf16 v[106:109], v[158:161], v[182:185], v[106:109]
	s_waitcnt lgkmcnt(0)
	v_mfma_f32_16x16x32_bf16 v[102:105], v[150:153], v[166:169], v[102:105]
	v_mfma_f32_16x16x32_bf16 v[98:101], v[158:161], v[166:169], v[98:101]
	s_setprio 0
	s_setprio 1
	s_setprio 0
	s_barrier
	s_mov_b32 m0, s37
	ds_read_b128 v[186:189], v216 offset:49152
	ds_read_b128 v[174:177], v216 offset:51200
	ds_read_b128 v[190:193], v217 offset:49152
	ds_read_b128 v[178:181], v217 offset:51200
	ds_read_b128 v[170:173], v216 offset:53248
	ds_read_b128 v[162:165], v216 offset:55296
	ds_read_b128 v[182:185], v217 offset:53248
	ds_read_b128 v[166:169], v217 offset:55296
	buffer_load_dwordx4 v203, s[8:11], s25 offen lds
	s_mov_b32 m0, s38
	s_and_b64 vcc, exec, s[2:3]
	buffer_load_dwordx4 v205, s[8:11], s25 offen lds
	s_add_i32 s25, s4, 0x10180
	s_mov_b32 m0, s42
	s_mov_b64 s[2:3], -1
	buffer_load_dwordx4 v203, s[8:11], s25 offen lds
	s_mov_b32 m0, s43
	s_nop 0
	buffer_load_dwordx4 v205, s[8:11], s25 offen lds
	s_mov_b32 m0, s40
	s_nop 0
	buffer_load_dwordx4 v198, s[8:11], s24 offen lds
	s_mov_b32 m0, s41
	s_nop 0
	buffer_load_dwordx4 v204, s[8:11], s24 offen lds
	s_cbranch_vccnz .LBB0_389
	s_waitcnt vmcnt(30)
	s_mov_b64 s[2:3], 0

.LBB0_391:
	s_waitcnt lgkmcnt(0)
	s_barrier
	s_setprio 1
	s_waitcnt lgkmcnt(7)
	v_mfma_f32_16x16x32_bf16 v[62:65], v[146:149], v[186:189], v[62:65]
	v_mfma_f32_16x16x32_bf16 v[58:61], v[154:157], v[186:189], v[58:61]
	s_waitcnt lgkmcnt(6)
	v_mfma_f32_16x16x32_bf16 v[54:57], v[146:149], v[174:177], v[54:57]
	v_mfma_f32_16x16x32_bf16 v[50:53], v[154:157], v[174:177], v[50:53]
	s_waitcnt lgkmcnt(3)
	v_mfma_f32_16x16x32_bf16 v[46:49], v[146:149], v[170:173], v[46:49]
	v_mfma_f32_16x16x32_bf16 v[42:45], v[154:157], v[170:173], v[42:45]
	s_waitcnt lgkmcnt(2)
	v_mfma_f32_16x16x32_bf16 v[38:41], v[146:149], v[162:165], v[38:41]
	v_mfma_f32_16x16x32_bf16 v[34:37], v[154:157], v[162:165], v[34:37]
	v_mfma_f32_16x16x32_bf16 v[62:65], v[150:153], v[190:193], v[62:65]
	v_mfma_f32_16x16x32_bf16 v[58:61], v[158:161], v[190:193], v[58:61]
	v_mfma_f32_16x16x32_bf16 v[54:57], v[150:153], v[178:181], v[54:57]
	v_mfma_f32_16x16x32_bf16 v[50:53], v[158:161], v[178:181], v[50:53]
	s_waitcnt lgkmcnt(1)
	v_mfma_f32_16x16x32_bf16 v[46:49], v[150:153], v[182:185], v[46:49]
	v_mfma_f32_16x16x32_bf16 v[42:45], v[158:161], v[182:185], v[42:45]
	s_waitcnt lgkmcnt(0)
	v_mfma_f32_16x16x32_bf16 v[38:41], v[150:153], v[166:169], v[38:41]
	v_mfma_f32_16x16x32_bf16 v[34:37], v[158:161], v[166:169], v[34:37]
	s_setprio 0
	s_setprio 1
	s_setprio 0
	s_barrier
	ds_read_b128 v[130:133], v208
	ds_read_b128 v[134:137], v209
	ds_read_b128 v[138:141], v210
	ds_read_b128 v[142:145], v211
	ds_read_b128 v[146:149], v212
	ds_read_b128 v[150:153], v213
	ds_read_b128 v[154:157], v214
	ds_read_b128 v[158:161], v215
	s_add_i32 s24, s55, s26
	s_and_b64 s[2:3], s[18:19], exec
	s_cselect_b32 s2, s24, s33
	s_mul_i32 s25, s2, 0x30000
	s_add_i32 s25, s25, 0xc000000
	s_and_b64 s[2:3], s[18:19], exec
	s_cselect_b32 s2, s25, s23
	s_lshl_b32 s3, s24, 12
	s_and_b32 s54, s3, 0xffff0000
	s_add_i32 s54, s54, 0x3000000
	s_and_b64 s[56:57], s[18:19], exec
	s_cselect_b32 s33, s54, s4
	s_add_i32 s3, s2, 0x80
	s_addk_i32 s23, 0xd80
	s_mov_b32 s4, s70
	s_mov_b32 m0, s44
	ds_read_b128 v[162:165], v216
	ds_read_b128 v[166:169], v216 offset:2048
	ds_read_b128 v[170:173], v217
	ds_read_b128 v[174:177], v217 offset:2048
	ds_read_b128 v[178:181], v216 offset:4096
	ds_read_b128 v[182:185], v216 offset:6144
	ds_read_b128 v[186:189], v217 offset:4096
	ds_read_b128 v[190:193], v217 offset:6144
	buffer_load_dwordx4 v198, s[4:7], s23 offen lds
	s_mov_b32 m0, s47
	s_nop 0
	buffer_load_dwordx4 v204, s[4:7], s23 offen lds
	s_waitcnt vmcnt(8)
	s_waitcnt lgkmcnt(0)
	s_barrier
	s_setprio 1
	s_waitcnt lgkmcnt(7)
	v_mfma_f32_16x16x32_bf16 v[126:129], v[130:133], v[162:165], v[126:129]
	v_mfma_f32_16x16x32_bf16 v[122:125], v[138:141], v[162:165], v[122:125]
	s_waitcnt lgkmcnt(6)
	v_mfma_f32_16x16x32_bf16 v[118:121], v[130:133], v[166:169], v[118:121]
	v_mfma_f32_16x16x32_bf16 v[114:117], v[138:141], v[166:169], v[114:117]
	s_waitcnt lgkmcnt(3)
	v_mfma_f32_16x16x32_bf16 v[110:113], v[130:133], v[178:181], v[110:113]
	v_mfma_f32_16x16x32_bf16 v[106:109], v[138:141], v[178:181], v[106:109]
	s_waitcnt lgkmcnt(2)
	v_mfma_f32_16x16x32_bf16 v[102:105], v[130:133], v[182:185], v[102:105]
	v_mfma_f32_16x16x32_bf16 v[98:101], v[138:141], v[182:185], v[98:101]
	v_mfma_f32_16x16x32_bf16 v[126:129], v[134:137], v[170:173], v[126:129]
	v_mfma_f32_16x16x32_bf16 v[122:125], v[142:145], v[170:173], v[122:125]
	v_mfma_f32_16x16x32_bf16 v[118:121], v[134:137], v[174:177], v[118:121]
	v_mfma_f32_16x16x32_bf16 v[114:117], v[142:145], v[174:177], v[114:117]
	s_waitcnt lgkmcnt(1)
	v_mfma_f32_16x16x32_bf16 v[110:113], v[134:137], v[186:189], v[110:113]
	v_mfma_f32_16x16x32_bf16 v[106:109], v[142:145], v[186:189], v[106:109]
	s_waitcnt lgkmcnt(0)
	v_mfma_f32_16x16x32_bf16 v[102:105], v[134:137], v[190:193], v[102:105]
	v_mfma_f32_16x16x32_bf16 v[98:101], v[142:145], v[190:193], v[98:101]
	s_setprio 0
	s_setprio 1
	s_setprio 0
	s_barrier
	s_mov_b32 m0, s28
	ds_read_b128 v[162:165], v216 offset:16384
	ds_read_b128 v[166:169], v216 offset:18432
	ds_read_b128 v[170:173], v217 offset:16384
	ds_read_b128 v[174:177], v217 offset:18432
	ds_read_b128 v[178:181], v216 offset:20480
	ds_read_b128 v[182:185], v216 offset:22528
	ds_read_b128 v[186:189], v217 offset:20480
	ds_read_b128 v[190:193], v217 offset:22528
	buffer_load_dwordx4 v203, s[4:7], s33 offen lds
	s_mov_b32 m0, s29
	s_add_i32 s23, s33, 0x10000
	buffer_load_dwordx4 v205, s[4:7], s33 offen lds
	s_mov_b32 m0, s30
	s_nop 0
	buffer_load_dwordx4 v203, s[4:7], s23 offen lds
	s_mov_b32 m0, s31
	s_nop 0
	buffer_load_dwordx4 v205, s[4:7], s23 offen lds
	s_mov_b32 m0, s27
	s_nop 0
	buffer_load_dwordx4 v198, s[4:7], s2 offen lds
	s_mov_b32 m0, s34
	s_nop 0
	buffer_load_dwordx4 v204, s[4:7], s2 offen lds
	s_waitcnt vmcnt(8)
	s_waitcnt lgkmcnt(0)
	s_barrier
	s_setprio 1
	s_waitcnt lgkmcnt(7)
	v_mfma_f32_16x16x32_bf16 v[62:65], v[130:133], v[162:165], v[62:65]
	v_mfma_f32_16x16x32_bf16 v[58:61], v[138:141], v[162:165], v[58:61]
	s_waitcnt lgkmcnt(6)
	v_mfma_f32_16x16x32_bf16 v[54:57], v[130:133], v[166:169], v[54:57]
	v_mfma_f32_16x16x32_bf16 v[50:53], v[138:141], v[166:169], v[50:53]
	s_waitcnt lgkmcnt(3)
	v_mfma_f32_16x16x32_bf16 v[46:49], v[130:133], v[178:181], v[46:49]
	v_mfma_f32_16x16x32_bf16 v[42:45], v[138:141], v[178:181], v[42:45]
	s_waitcnt lgkmcnt(2)
	v_mfma_f32_16x16x32_bf16 v[38:41], v[130:133], v[182:185], v[38:41]
	v_mfma_f32_16x16x32_bf16 v[34:37], v[138:141], v[182:185], v[34:37]
	v_mfma_f32_16x16x32_bf16 v[62:65], v[134:137], v[170:173], v[62:65]
	v_mfma_f32_16x16x32_bf16 v[58:61], v[142:145], v[170:173], v[58:61]
	v_mfma_f32_16x16x32_bf16 v[54:57], v[134:137], v[174:177], v[54:57]
	v_mfma_f32_16x16x32_bf16 v[50:53], v[142:145], v[174:177], v[50:53]
	s_waitcnt lgkmcnt(1)
	v_mfma_f32_16x16x32_bf16 v[46:49], v[134:137], v[186:189], v[46:49]
	v_mfma_f32_16x16x32_bf16 v[42:45], v[142:145], v[186:189], v[42:45]
	s_waitcnt lgkmcnt(0)
	v_mfma_f32_16x16x32_bf16 v[38:41], v[134:137], v[190:193], v[38:41]
	v_mfma_f32_16x16x32_bf16 v[34:37], v[142:145], v[190:193], v[34:37]
	s_setprio 0
	s_setprio 1
	s_setprio 0
	s_barrier
	ds_read_b128 v[130:133], v218
	ds_read_b128 v[134:137], v219
	ds_read_b128 v[138:141], v220
	ds_read_b128 v[142:145], v221
	ds_read_b128 v[146:149], v222
	ds_read_b128 v[150:153], v223
	ds_read_b128 v[154:157], v224
	ds_read_b128 v[158:161], v225
	s_add_i32 s23, s2, 0xc00
	s_mov_b32 m0, s35
	ds_read_b128 v[162:165], v216 offset:32768
	ds_read_b128 v[166:169], v216 offset:34816
	ds_read_b128 v[170:173], v217 offset:32768
	ds_read_b128 v[174:177], v217 offset:34816
	ds_read_b128 v[178:181], v216 offset:36864
	ds_read_b128 v[182:185], v216 offset:38912
	ds_read_b128 v[186:189], v217 offset:36864
	ds_read_b128 v[190:193], v217 offset:38912
	buffer_load_dwordx4 v198, s[4:7], s23 offen lds
	s_mov_b32 m0, s36
	s_nop 0
	buffer_load_dwordx4 v204, s[4:7], s23 offen lds
	s_waitcnt vmcnt(8)
	s_waitcnt lgkmcnt(0)
	s_barrier
	s_setprio 1
	s_waitcnt lgkmcnt(7)
	v_mfma_f32_16x16x32_bf16 v[126:129], v[130:133], v[162:165], v[126:129]
	v_mfma_f32_16x16x32_bf16 v[122:125], v[138:141], v[162:165], v[122:125]
	s_waitcnt lgkmcnt(6)
	v_mfma_f32_16x16x32_bf16 v[118:121], v[130:133], v[166:169], v[118:121]
	v_mfma_f32_16x16x32_bf16 v[114:117], v[138:141], v[166:169], v[114:117]
	s_waitcnt lgkmcnt(3)
	v_mfma_f32_16x16x32_bf16 v[110:113], v[130:133], v[178:181], v[110:113]
	v_mfma_f32_16x16x32_bf16 v[106:109], v[138:141], v[178:181], v[106:109]
	s_waitcnt lgkmcnt(2)
	v_mfma_f32_16x16x32_bf16 v[102:105], v[130:133], v[182:185], v[102:105]
	v_mfma_f32_16x16x32_bf16 v[98:101], v[138:141], v[182:185], v[98:101]
	v_mfma_f32_16x16x32_bf16 v[126:129], v[134:137], v[170:173], v[126:129]
	v_mfma_f32_16x16x32_bf16 v[122:125], v[142:145], v[170:173], v[122:125]
	v_mfma_f32_16x16x32_bf16 v[118:121], v[134:137], v[174:177], v[118:121]
	v_mfma_f32_16x16x32_bf16 v[114:117], v[142:145], v[174:177], v[114:117]
	s_waitcnt lgkmcnt(1)
	v_mfma_f32_16x16x32_bf16 v[110:113], v[134:137], v[186:189], v[110:113]
	v_mfma_f32_16x16x32_bf16 v[106:109], v[142:145], v[186:189], v[106:109]
	s_waitcnt lgkmcnt(0)
	v_mfma_f32_16x16x32_bf16 v[102:105], v[134:137], v[190:193], v[102:105]
	v_mfma_f32_16x16x32_bf16 v[98:101], v[142:145], v[190:193], v[98:101]
	s_setprio 0
	s_setprio 1
	s_setprio 0
	s_barrier
	s_mov_b32 m0, s37
	s_add_i32 s23, s33, 0x80
	ds_read_b128 v[162:165], v216 offset:49152
	ds_read_b128 v[166:169], v216 offset:51200
	ds_read_b128 v[170:173], v217 offset:49152
	ds_read_b128 v[174:177], v217 offset:51200
	ds_read_b128 v[178:181], v216 offset:53248
	ds_read_b128 v[182:185], v216 offset:55296
	ds_read_b128 v[186:189], v217 offset:53248
	ds_read_b128 v[190:193], v217 offset:55296
	buffer_load_dwordx4 v203, s[4:7], s23 offen lds
	s_mov_b32 m0, s38
	s_add_i32 s33, s33, 0x10080
	buffer_load_dwordx4 v205, s[4:7], s23 offen lds
	s_mov_b32 m0, s42
	s_nop 0
	buffer_load_dwordx4 v203, s[4:7], s33 offen lds
	s_mov_b32 m0, s43
	s_nop 0
	buffer_load_dwordx4 v205, s[4:7], s33 offen lds
	s_mov_b32 m0, s40
	s_nop 0
	buffer_load_dwordx4 v198, s[4:7], s3 offen lds
	s_mov_b32 m0, s41
	s_nop 0
	buffer_load_dwordx4 v204, s[4:7], s3 offen lds
	s_waitcnt vmcnt(8)
	s_waitcnt lgkmcnt(0)
	s_barrier
	s_setprio 1
	s_waitcnt lgkmcnt(7)
	v_mfma_f32_16x16x32_bf16 v[62:65], v[130:133], v[162:165], v[62:65]
	v_mfma_f32_16x16x32_bf16 v[58:61], v[138:141], v[162:165], v[58:61]
	s_waitcnt lgkmcnt(6)
	v_mfma_f32_16x16x32_bf16 v[54:57], v[130:133], v[166:169], v[54:57]
	v_mfma_f32_16x16x32_bf16 v[50:53], v[138:141], v[166:169], v[50:53]
	s_waitcnt lgkmcnt(3)
	v_mfma_f32_16x16x32_bf16 v[46:49], v[130:133], v[178:181], v[46:49]
	v_mfma_f32_16x16x32_bf16 v[42:45], v[138:141], v[178:181], v[42:45]
	s_waitcnt lgkmcnt(2)
	v_mfma_f32_16x16x32_bf16 v[38:41], v[130:133], v[182:185], v[38:41]
	v_mfma_f32_16x16x32_bf16 v[34:37], v[138:141], v[182:185], v[34:37]
	v_mfma_f32_16x16x32_bf16 v[62:65], v[134:137], v[170:173], v[62:65]
	v_mfma_f32_16x16x32_bf16 v[58:61], v[142:145], v[170:173], v[58:61]
	v_mfma_f32_16x16x32_bf16 v[54:57], v[134:137], v[174:177], v[54:57]
	v_mfma_f32_16x16x32_bf16 v[50:53], v[142:145], v[174:177], v[50:53]
	s_waitcnt lgkmcnt(1)
	v_mfma_f32_16x16x32_bf16 v[46:49], v[134:137], v[186:189], v[46:49]
	v_mfma_f32_16x16x32_bf16 v[42:45], v[142:145], v[186:189], v[42:45]
	s_waitcnt lgkmcnt(0)
	v_mfma_f32_16x16x32_bf16 v[38:41], v[134:137], v[190:193], v[38:41]
	v_mfma_f32_16x16x32_bf16 v[34:37], v[142:145], v[190:193], v[34:37]
	s_setprio 0
	s_setprio 1
	s_setprio 0
	s_barrier
	s_andn2_b64 vcc, exec, s[16:17]
	s_cbranch_vccnz .LBB0_393
	s_barrier
